# setup phase: SSM kernel-table (KTAB) inner loop software-pipelined two-deep with alternating register sets (next iteration's 8 loads in flight during the current iteration's math; same summation order
# baseline (speedup 1.0000x reference)
; __device__ __forceinline__ void ssm_tables1(ArgsP a, int gt, int NGT) {
;     ...
;         const int hp = o & 15, h = (o >> 4) & 15, tau = (o >> 8) & 31, q = o >> 13; float s = 0.f;
;         for (int p = 0; p < 64; ++p) { const float cr = a->C_re[(size_t)q * 1024 + h * 64 + p], ci = a->C_im[(size_t)q * 1024 + h * 64 + p];
;             const float2 l = LP[(size_t)(q * 33 + tau) * 64 + p], b = BB[((size_t)q * 64 + p) * 16 + hp];
;             const float xr = l.x * b.x - l.y * b.y, xi = l.x * b.y + l.y * b.x; s += cr * xr - ci * xi; }
;         KT[o] = s;
.Lkt_loop:
	v_lshl_add_u64 v[82:83], s[16:17], 0, v[10:11]
	v_add_co_u32_e32 v88, vcc, 0x36100000, v82
	v_lshl_add_u64 v[80:81], s[16:17], 0, v[12:13]
	s_nop 0
	v_addc_co_u32_e32 v89, vcc, 0, v83, vcc
	v_lshl_add_u64 v[76:77], v[14:15], 0, s[24:25]
	v_lshl_add_u64 v[78:79], v[16:17], 0, s[24:25]
	v_add_co_u32_e32 v90, vcc, 0x35d00000, v80
	global_load_dwordx4 v[68:71], v[76:77], off
	global_load_dwordx4 v[72:75], v[78:79], off
	v_lshl_add_u64 v[86:87], v[80:81], 0, s[18:19]
	v_addc_co_u32_e32 v91, vcc, 0, v81, vcc
	global_load_dwordx2 v[92:93], v[88:89], off
	global_load_dwordx4 v[76:79], v[86:87], off offset:16
	global_load_dwordx2 v[94:95], v[88:89], off offset:128
	global_load_dwordx2 v[96:97], v[88:89], off offset:256
	global_load_dwordx4 v[80:83], v[90:91], off
	global_load_dwordx2 v[98:99], v[88:89], off offset:384
	s_add_u32 s24, s24, 16
	s_addc_u32 s25, s25, 0
	v_lshl_add_u64 v[10:11], v[10:11], 0, s[22:23]
	v_lshl_add_u64 v[12:13], v[12:13], 0, 32
	s_waitcnt vmcnt(8)
	v_mov_b32_e32 v36, v18
	v_mov_b32_e32 v37, v22
	v_mov_b32_e32 v22, v19
	v_mov_b32_e32 v18, v20
	v_mov_b32_e32 v19, v24
	v_mov_b32_e32 v24, v21
	v_pk_mul_f32 v[20:21], v[26:27], v[46:47] op_sel:[1,1] op_sel_hi:[0,1]
	v_pk_mul_f32 v[38:39], v[28:29], v[48:49] op_sel:[1,1] op_sel_hi:[0,1]
	v_pk_mul_f32 v[40:41], v[30:31], v[42:43] op_sel:[1,1] op_sel_hi:[0,1]
	v_pk_mul_f32 v[50:51], v[32:33], v[44:45] op_sel:[1,1] op_sel_hi:[0,1]
	v_pk_fma_f32 v[52:53], v[26:27], v[46:47], v[20:21] neg_lo:[0,0,1] neg_hi:[0,0,1]
	v_pk_fma_f32 v[20:21], v[26:27], v[46:47], v[20:21] op_sel_hi:[1,0,1]
	v_pk_fma_f32 v[26:27], v[28:29], v[48:49], v[38:39] neg_lo:[0,0,1] neg_hi:[0,0,1]
	v_pk_fma_f32 v[28:29], v[28:29], v[48:49], v[38:39] op_sel_hi:[1,0,1]
	v_pk_fma_f32 v[38:39], v[30:31], v[42:43], v[40:41] neg_lo:[0,0,1] neg_hi:[0,0,1]
	v_pk_fma_f32 v[30:31], v[30:31], v[42:43], v[40:41] op_sel_hi:[1,0,1]
	v_pk_fma_f32 v[40:41], v[32:33], v[44:45], v[50:51] neg_lo:[0,0,1] neg_hi:[0,0,1]
	v_pk_fma_f32 v[32:33], v[32:33], v[44:45], v[50:51] op_sel_hi:[1,0,1]
	v_mov_b32_e32 v53, v21
	v_mov_b32_e32 v27, v29
	v_mov_b32_e32 v39, v31
	v_mov_b32_e32 v41, v33
	v_pk_mul_f32 v[18:19], v[18:19], v[52:53]
	v_pk_mul_f32 v[20:21], v[24:25], v[26:27]
	v_pk_mul_f32 v[24:25], v[36:37], v[38:39]
	v_pk_mul_f32 v[22:23], v[22:23], v[40:41]
	v_sub_f32_e32 v7, v18, v19
	v_sub_f32_e32 v18, v24, v25
	v_sub_f32_e32 v19, v22, v23
	v_add_f32_e32 v4, v4, v18
	v_add_f32_e32 v4, v4, v19
	v_sub_f32_e32 v9, v20, v21
	v_add_f32_e32 v4, v4, v7
	v_add_f32_e32 v4, v4, v9
	s_cmpk_eq_i32 s24, 0x100
	s_cbranch_scc1 .Lkt_last
	v_lshl_add_u64 v[32:33], s[16:17], 0, v[10:11]
	v_add_co_u32_e32 v38, vcc, 0x36100000, v32
	v_lshl_add_u64 v[30:31], s[16:17], 0, v[12:13]
	s_nop 0
	v_addc_co_u32_e32 v39, vcc, 0, v33, vcc
	v_lshl_add_u64 v[26:27], v[14:15], 0, s[24:25]
	v_lshl_add_u64 v[28:29], v[16:17], 0, s[24:25]
	v_add_co_u32_e32 v40, vcc, 0x35d00000, v30
	global_load_dwordx4 v[18:21], v[26:27], off
	global_load_dwordx4 v[22:25], v[28:29], off
	v_lshl_add_u64 v[36:37], v[30:31], 0, s[18:19]
	v_addc_co_u32_e32 v41, vcc, 0, v31, vcc
	global_load_dwordx2 v[42:43], v[38:39], off
	global_load_dwordx4 v[26:29], v[36:37], off offset:16
	global_load_dwordx2 v[44:45], v[38:39], off offset:128
	global_load_dwordx2 v[46:47], v[38:39], off offset:256
	global_load_dwordx4 v[30:33], v[40:41], off
	global_load_dwordx2 v[48:49], v[38:39], off offset:384
	s_add_u32 s24, s24, 16
	s_addc_u32 s25, s25, 0
	v_lshl_add_u64 v[10:11], v[10:11], 0, s[22:23]
	v_lshl_add_u64 v[12:13], v[12:13], 0, 32
	s_waitcnt vmcnt(8)
	v_mov_b32_e32 v86, v68
	v_mov_b32_e32 v87, v72
	v_mov_b32_e32 v72, v69
	v_mov_b32_e32 v68, v70
	v_mov_b32_e32 v69, v74
	v_mov_b32_e32 v74, v71
	v_pk_mul_f32 v[70:71], v[76:77], v[96:97] op_sel:[1,1] op_sel_hi:[0,1]
	v_pk_mul_f32 v[88:89], v[78:79], v[98:99] op_sel:[1,1] op_sel_hi:[0,1]
	v_pk_mul_f32 v[90:91], v[80:81], v[92:93] op_sel:[1,1] op_sel_hi:[0,1]
	v_pk_mul_f32 v[100:101], v[82:83], v[94:95] op_sel:[1,1] op_sel_hi:[0,1]
	v_pk_fma_f32 v[102:103], v[76:77], v[96:97], v[70:71] neg_lo:[0,0,1] neg_hi:[0,0,1]
	v_pk_fma_f32 v[70:71], v[76:77], v[96:97], v[70:71] op_sel_hi:[1,0,1]
	v_pk_fma_f32 v[76:77], v[78:79], v[98:99], v[88:89] neg_lo:[0,0,1] neg_hi:[0,0,1]
	v_pk_fma_f32 v[78:79], v[78:79], v[98:99], v[88:89] op_sel_hi:[1,0,1]
	v_pk_fma_f32 v[88:89], v[80:81], v[92:93], v[90:91] neg_lo:[0,0,1] neg_hi:[0,0,1]
	v_pk_fma_f32 v[80:81], v[80:81], v[92:93], v[90:91] op_sel_hi:[1,0,1]
	v_pk_fma_f32 v[90:91], v[82:83], v[94:95], v[100:101] neg_lo:[0,0,1] neg_hi:[0,0,1]
	v_pk_fma_f32 v[82:83], v[82:83], v[94:95], v[100:101] op_sel_hi:[1,0,1]
	v_mov_b32_e32 v103, v71
	v_mov_b32_e32 v77, v79
	v_mov_b32_e32 v89, v81
	v_mov_b32_e32 v91, v83
	v_pk_mul_f32 v[68:69], v[68:69], v[102:103]
	v_pk_mul_f32 v[70:71], v[74:75], v[76:77]
	v_pk_mul_f32 v[74:75], v[86:87], v[88:89]
	v_pk_mul_f32 v[72:73], v[72:73], v[90:91]
	v_sub_f32_e32 v57, v68, v69
	v_sub_f32_e32 v68, v74, v75
	v_sub_f32_e32 v69, v72, v73
	v_add_f32_e32 v4, v4, v68
	v_add_f32_e32 v4, v4, v69
	v_sub_f32_e32 v59, v70, v71
	v_add_f32_e32 v4, v4, v57
	v_add_f32_e32 v4, v4, v59
	s_branch .Lkt_loop
; __device__ __forceinline__ void ssm_tables1(ArgsP a, int gt, int NGT) {
;     ...
;         for (int p = 0; p < 64; ++p) { const float cr = a->C_re[(size_t)q * 1024 + h * 64 + p], ci = a->C_im[(size_t)q * 1024 + h * 64 + p];
;             const float2 l = LP[(size_t)(q * 33 + tau) * 64 + p], b = BB[((size_t)q * 64 + p) * 16 + hp];
;             const float xr = l.x * b.x - l.y * b.y, xi = l.x * b.y + l.y * b.x; s += cr * xr - ci * xi; }
;         KT[o] = s;
;     }
;     for (int o = gt; o < 2 * 32 * 256 * 64; o += NGT) {
;         const int half = o & 1, s = (o >> 1) & 31, n = (o >> 6) & 255, ig = o >> 14, i = ig >> 5, g = ig & 31;
;         const int dir = n >> 7, part = (n >> 6) & 1, p = n & 63, q = (i * 2 + dir) * 32 + g, e = dir == 0 ? 31 - s : s;
;         const float2 l = LP[(size_t)(q * 33 + e) * 64 + p]; float v[8];
.Lkt_last:
	s_waitcnt vmcnt(0)
	v_mov_b32_e32 v86, v68
	v_mov_b32_e32 v87, v72
	v_mov_b32_e32 v72, v69
	v_mov_b32_e32 v68, v70
	v_mov_b32_e32 v69, v74
	v_mov_b32_e32 v74, v71
	v_pk_mul_f32 v[70:71], v[76:77], v[96:97] op_sel:[1,1] op_sel_hi:[0,1]
	v_pk_mul_f32 v[88:89], v[78:79], v[98:99] op_sel:[1,1] op_sel_hi:[0,1]
	v_pk_mul_f32 v[90:91], v[80:81], v[92:93] op_sel:[1,1] op_sel_hi:[0,1]
	v_pk_mul_f32 v[100:101], v[82:83], v[94:95] op_sel:[1,1] op_sel_hi:[0,1]
	v_pk_fma_f32 v[102:103], v[76:77], v[96:97], v[70:71] neg_lo:[0,0,1] neg_hi:[0,0,1]
	v_pk_fma_f32 v[70:71], v[76:77], v[96:97], v[70:71] op_sel_hi:[1,0,1]
	v_pk_fma_f32 v[76:77], v[78:79], v[98:99], v[88:89] neg_lo:[0,0,1] neg_hi:[0,0,1]
	v_pk_fma_f32 v[78:79], v[78:79], v[98:99], v[88:89] op_sel_hi:[1,0,1]
	v_pk_fma_f32 v[88:89], v[80:81], v[92:93], v[90:91] neg_lo:[0,0,1] neg_hi:[0,0,1]
	v_pk_fma_f32 v[80:81], v[80:81], v[92:93], v[90:91] op_sel_hi:[1,0,1]
	v_pk_fma_f32 v[90:91], v[82:83], v[94:95], v[100:101] neg_lo:[0,0,1] neg_hi:[0,0,1]
	v_pk_fma_f32 v[82:83], v[82:83], v[94:95], v[100:101] op_sel_hi:[1,0,1]
	v_mov_b32_e32 v103, v71
	v_mov_b32_e32 v77, v79
	v_mov_b32_e32 v89, v81
	v_mov_b32_e32 v91, v83
	v_pk_mul_f32 v[68:69], v[68:69], v[102:103]
	v_pk_mul_f32 v[70:71], v[74:75], v[76:77]
	v_pk_mul_f32 v[74:75], v[86:87], v[88:89]
	v_pk_mul_f32 v[72:73], v[72:73], v[90:91]
	v_sub_f32_e32 v57, v68, v69
	v_sub_f32_e32 v68, v74, v75
	v_sub_f32_e32 v69, v72, v73
	v_add_f32_e32 v4, v4, v68
	v_add_f32_e32 v4, v4, v69
	v_sub_f32_e32 v59, v70, v71
	v_add_f32_e32 v4, v4, v57
	v_add_f32_e32 v4, v4, v59
	v_ashrrev_i32_e32 v9, 31, v8
	v_readlane_b32 s24, v253, 2
	v_lshl_add_u64 v[10:11], v[8:9], 2, s[4:5]
	v_add_u32_e32 v3, s26, v3
	v_add_u32_e32 v8, s24, v8
	v_cmp_lt_i32_e32 vcc, s28, v8
	s_or_b64 s[6:7], vcc, s[6:7]
	global_store_dword v[10:11], v4, off
	v_readlane_b32 s25, v253, 3
	s_andn2_b64 exec, exec, s[6:7]
	s_cbranch_execnz .LBB0_77
	s_or_b64 exec, exec, s[6:7]
	s_add_u32 s6, s16, 0x35d00000
	s_addc_u32 s7, s17, 0
	s_add_u32 s4, s16, 0x36100000
	s_addc_u32 s5, s17, 0
	v_lshlrev_b32_e32 v2, 3, v34
	s_add_u32 s18, s16, 0x34d00000
	v_lshl_add_u32 v7, s2, 12, v2
	s_addc_u32 s19, s17, 0
	s_lshl_b32 s24, s50, 12
	s_mov_b64 s[22:23], 0
	s_mov_b32 s25, 0x7fffffe
	s_movk_i32 s26, 0x80
	v_mov_b32_e32 v3, 0
	s_mov_b32 s27, 0xfffff
	v_mov_b32_e32 v4, v7
	v_mov_b32_e32 v5, v6
	v_readlane_b32 s28, v253, 2
	v_readlane_b32 s29, v253, 3
